# P4 tile order permuted so every workgroup gets one Q, K, V and ZS column tile (the silu epilogue of ZS tiles ran twice on half the workgroups and never on the rest)
# speedup vs baseline: 1.0049x; 1.0028x over previous
; __device__ __forceinline__ int tid_of(int wave) { return wave * 64 + lane_id(); }
; #define PG8_STAGE(bufoff, gbase, voff) do { _Pragma("unroll") for (int _i = 0; _i < 2; ++_i) \
;         __builtin_amdgcn_global_load_lds((const unsigned*)((const char*)(gbase) + (voff)[_i]), (PG8_LAS unsigned*)(lds + (bufoff) + ldsw + _i * 8192), 16, 0, 0); } while (0)
; #define PG8_WAIT_V(n) asm volatile("s_waitcnt vmcnt(" #n ")" ::: "memory")
; #define PG8_BAR __builtin_amdgcn_s_barrier()
; #define tid tid_of(wave)
; #define lane lane_id()
; template <class Epi, class Sched, bool ALIGN_EPI = false, bool SP2 = false>
; __device__ __forceinline__ void gemm_phase(PG8_LAS unsigned char* lds, const Gemm g, const Sched& S, const Epi& E, const int wave_) {
;     const int tid = tid_of(wave_), wid = wave_, lane = tid & 63, wr = wid >> 2, wc = wid & 3, fr = lane & 15, fq = lane >> 4;
;     const int K = g.K, nt = K / BK;
;     unsigned voffA[2], voffB[2];
; #pragma unroll
;     for (int i = 0; i < 2; ++i) { int R, C; stage_rc(tid * 16 + i * 8192, R, C); const int Rb = Epi::PERM ? ((R & ~31) + perm32(R & 31)) : R;
;         voffA[i] = (unsigned)(R * K + C) * 2u; voffB[i] = (unsigned)(Rb * K + C) * 2u; }
;     const size_t kstep = (size_t)(BK * 2);
;     const size_t hstep = (size_t)HALF * K * 2;
;     const size_t tstep = 2 * hstep;
;     const unsigned ldsw = (unsigned)wid * 1024u;
;     const int aoff = lds_byte(wr * 64 + fr, fq * 8), boff = lds_byte(wc * 32 + fr, fq * 8);
;     ...
;     const char* cA = (const char*)g.A + (size_t)cur.pm * tstep; const char* cB = (const char*)g.Bt + (size_t)cur.pn * tstep;
;     S.a_ready(cur);
;     if constexpr (SP2) {
;         PG8_STAGE(PG8_SB(0, 0), cB, voffB); PG8_STAGE(PG8_SB(0, 1), cB + hstep, voffB); PG8_STAGE(PG8_SA(0, 0), cA, voffA); PG8_STAGE(PG8_SA(0, 1), cA + hstep, voffA);
;         if (wr == 1) PG8_BAR;
;         PG8_WAIT_V(2); PG8_BAR;
;         PG8_STAGE(PG8_SB(1, 0), cB + kstep, voffB); PG8_STAGE(PG8_SA(1, 0), cA + kstep, voffA); PG8_STAGE(PG8_SB(1, 1), cB + hstep + kstep, voffB);
;         PG8_WAIT_V(6); PG8_BAR;
;     } else {
;         PG8_STAGE(PG8_SB(0, 0), cB, voffB); PG8_STAGE(PG8_SA(0, 0), cA, voffA); PG8_STAGE(PG8_SB(0, 1), cB + hstep, voffB); PG8_STAGE(PG8_SA(0, 1), cA + hstep, voffA);
;         if (wr == 1) PG8_BAR;
;         PG8_WAIT_V(4); PG8_BAR;
.LBB0_482:
	s_andn2_b64 vcc, exec, s[0:1]
	s_cbranch_vccnz .LBB0_534
	s_lshr_b32 s98, s6, 2
	s_add_i32 s99, s6, s98
	s_and_b32 s99, s99, 3
	s_lshl_b32 s99, s99, 3
	s_and_b32 s98, s98, 3
	s_add_i32 s99, s99, s98
	s_lshr_b32 s98, s6, 4
	s_lshl_b32 s98, s98, 2
	s_add_i32 s6, s99, s98
	v_readlane_b32 s1, v248, 22
	s_lshl_b32 s44, s1, 10
	v_lshl_add_u32 v0, v195, 4, s44
	s_waitcnt lgkmcnt(0)
	v_ashrrev_i32_e32 v1, 31, v0
	v_lshrrev_b32_e32 v1, 22, v1
	v_add_u32_e32 v1, v0, v1
	v_ashrrev_i32_e32 v8, 10, v1
	v_mul_i32_i24_e32 v1, 0x400, v8
	v_sub_u32_e32 v1, v0, v1
	v_lshrrev_b32_e32 v2, 4, v1
	v_bitop3_b32 v1, v2, v1, 32 bitop3:0x6c
	v_ashrrev_i32_e32 v3, 31, v1
	v_lshrrev_b32_e32 v3, 26, v3
	v_add_u32_e32 v3, v1, v3
	v_lshlrev_b32_e32 v2, 3, v8
	v_ashrrev_i32_e32 v9, 6, v3
	v_and_b32_e32 v3, 0xc0, v3
	v_and_b32_e32 v2, -16, v2
	v_sub_u32_e32 v1, v1, v3
	v_mov_b32_e32 v3, 1
	v_add_u32_e32 v2, v9, v2
	v_ashrrev_i16_sdwa v1, v3, sext(v1) dst_sel:DWORD dst_unused:UNUSED_PAD src0_sel:DWORD src1_sel:BYTE_0
	v_lshlrev_b32_e32 v4, 5, v8
	v_bfe_i32 v10, v1, 0, 16
	v_lshlrev_b32_e32 v1, 1, v2
	v_lshrrev_b32_e32 v5, 2, v2
	v_and_b32_e32 v6, 3, v9
	s_mov_b32 s1, 0xfffe0
	v_and_b32_e32 v4, 32, v4
	v_and_b32_e32 v1, 24, v1
	v_and_b32_e32 v5, 4, v5
	v_and_or_b32 v6, v2, s1, v6
	v_or3_b32 v1, v6, v5, v1
	v_add_lshl_u32 v4, v4, v10, 1
	v_add_u32_e32 v0, 0x2000, v0
	v_lshl_add_u32 v130, v1, 12, v4
	v_ashrrev_i32_e32 v1, 31, v0
	v_lshrrev_b32_e32 v1, 22, v1
	v_add_u32_e32 v1, v0, v1
	v_ashrrev_i32_e32 v11, 10, v1
	v_mul_i32_i24_e32 v1, 0x400, v11
	v_sub_u32_e32 v0, v0, v1
	v_lshrrev_b32_e32 v1, 4, v0
	v_bitop3_b32 v0, v1, v0, 32 bitop3:0x6c
	v_lshl_add_u32 v128, v2, 12, v4
	v_ashrrev_i32_e32 v2, 31, v0
	v_lshrrev_b32_e32 v2, 26, v2
	v_add_u32_e32 v2, v0, v2
	v_ashrrev_i32_e32 v12, 6, v2
	v_and_b32_e32 v2, 0xffc0, v2
	s_lshr_b32 s0, s67, 8
	v_sub_u32_e32 v0, v0, v2
	v_lshrrev_b16_e32 v2, 7, v0
	s_cmp_eq_u32 s0, 1
	v_lshlrev_b32_e32 v1, 3, v11
	v_and_b32_e32 v2, 1, v2
	s_cselect_b64 s[12:13], -1, 0
	s_ashr_i32 s5, s4, 31
	s_ashr_i32 s7, s6, 31
	v_and_b32_e32 v1, -16, v1
	v_add_u16_e32 v0, v0, v2
	s_lshl_b64 s[14:15], s[4:5], 20
	s_lshl_b64 s[16:17], s[6:7], 20
	v_readlane_b32 s18, v248, 31
	v_add_u32_e32 v1, v12, v1
	v_ashrrev_i16_sdwa v0, v3, sext(v0) dst_sel:DWORD dst_unused:UNUSED_PAD src0_sel:DWORD src1_sel:BYTE_0
	v_readlane_b32 s19, v248, 32
	s_add_u32 s40, s18, s16
	v_lshlrev_b32_e32 v4, 5, v11
	v_bfe_i32 v13, v0, 0, 16
	v_lshlrev_b32_e32 v0, 1, v1
	v_lshrrev_b32_e32 v2, 2, v1
	v_and_b32_e32 v3, 3, v12
	s_addc_u32 s41, s19, s17
	s_add_i32 s45, s44, 0
	v_and_b32_e32 v4, 32, v4
	v_and_b32_e32 v0, 24, v0
	v_and_b32_e32 v2, 4, v2
	v_and_or_b32 v3, v1, s1, v3
	s_add_i32 m0, s45, 0x10000
	s_add_i32 s1, s45, 0x12000
	v_or3_b32 v0, v3, v2, v0
	v_add_lshl_u32 v2, v4, v13, 1
	s_add_u32 s16, s40, 0x80000
	v_lshl_add_u32 v134, v0, 12, v2
	s_addc_u32 s17, s41, 0
	s_add_i32 s5, s45, 0x14000
	s_add_i32 s7, s45, 0x16000
	global_load_lds_dwordx4 v130, s[40:41]
	s_mov_b32 m0, s1
	s_add_u32 s36, s38, s14
	global_load_lds_dwordx4 v134, s[40:41]
	s_mov_b32 m0, s5
	s_addc_u32 s37, s39, s15
	s_add_i32 s46, s45, 0x2000
	global_load_lds_dwordx4 v130, s[16:17]
	s_mov_b32 m0, s7
	s_add_u32 s14, s36, 0x80000
	global_load_lds_dwordx4 v134, s[16:17]
	s_mov_b32 m0, s45
	v_lshl_add_u32 v132, v1, 12, v2
	s_addc_u32 s15, s37, 0
	s_add_i32 s47, s45, 0x4000
	global_load_lds_dwordx4 v128, s[36:37]
	s_mov_b32 m0, s46
	s_add_i32 s48, s45, 0x6000
	global_load_lds_dwordx4 v132, s[36:37]
	s_mov_b32 m0, s47
	v_mov_b32_e32 v137, 0
	global_load_lds_dwordx4 v128, s[14:15]
	s_mov_b32 m0, s48
	v_mov_b32_e32 v131, v137
	global_load_lds_dwordx4 v132, s[14:15]
	v_mov_b32_e32 v135, v137
	v_mov_b32_e32 v129, v137
	v_mov_b32_e32 v133, v137
	s_mov_b32 s49, 0
	s_mov_b64 s[14:15], 0x80000
	s_cmp_lg_u32 s0, 1
	v_lshl_add_u64 v[6:7], s[40:41], 0, v[130:131]
	v_lshl_add_u64 v[4:5], s[40:41], 0, v[134:135]
	v_lshl_add_u64 v[2:3], s[36:37], 0, v[128:129]
	v_lshl_add_u64 v[0:1], s[36:37], 0, v[132:133]
	s_cbranch_scc1 .LBB0_485
	s_barrier

;     __host__ __device__ bool next(int i, Unit& u) const {
;         const long L = (long)i * G + c; if (L >= nwg) return false;
;         int wgid = (int)L; { const int q = nwg / NXCD, r = nwg % NXCD, xcd = wgid % NXCD, off = wgid / NXCD; wgid = (xcd < r ? xcd * (q + 1) : r * (q + 1) + (xcd - r) * q) + off; }
;         const int nig = WGM * nN, gid = wgid / nig, fm = gid * WGM, gsz = (nM - fm) < WGM ? (nM - fm) : WGM;
;         u.pm = fm + ((wgid % nig) % gsz); u.pn = (wgid % nig) / gsz; return true;
.LBB0_493:
	s_ashr_i32 s5, s5, 3
	s_add_i32 s5, s28, s5
	s_ashr_i32 s7, s5, 31
	s_lshr_b32 s7, s7, 24
	s_add_i32 s7, s5, s7
	s_ashr_i32 s26, s7, 8
	s_lshl_b32 s27, s26, 3
	s_sub_i32 s26, 32, s27
	s_min_i32 s28, s26, 8
	s_abs_i32 s26, s28
	v_cvt_f32_u32_e32 v0, s26
	s_sub_i32 s30, 0, s26
	s_and_b32 s7, s7, 0xffffff00
	s_sub_i32 s5, s5, s7
	v_rcp_iflag_f32_e32 v0, v0
	s_abs_i32 s7, s5
	s_xor_b32 s29, s5, s28
	s_ashr_i32 s29, s29, 31
	v_mul_f32_e32 v0, 0x4f7ffffe, v0
	v_cvt_u32_f32_e32 v0, v0
	s_nop 0
	v_readfirstlane_b32 s31, v0
	s_mul_i32 s30, s30, s31
	s_mul_hi_u32 s30, s31, s30
	s_add_i32 s31, s31, s30
	s_mul_hi_u32 s30, s7, s31
	s_mul_i32 s31, s30, s26
	s_sub_i32 s7, s7, s31
	s_add_i32 s34, s30, 1
	s_sub_i32 s31, s7, s26
	s_cmp_ge_u32 s7, s26
	s_cselect_b32 s30, s34, s30
	s_cselect_b32 s7, s31, s7
	s_add_i32 s31, s30, 1
	s_cmp_ge_u32 s7, s26
	s_cselect_b32 s7, s31, s30
	s_xor_b32 s7, s7, s29
	s_sub_i32 s26, s7, s29
	s_mul_i32 s7, s26, s28
	s_sub_i32 s5, s5, s7
	s_add_i32 s28, s27, s5
	s_lshr_b32 s98, s26, 2
	s_add_i32 s99, s26, s98
	s_and_b32 s99, s99, 3
	s_lshl_b32 s99, s99, 3
	s_and_b32 s98, s98, 3
	s_add_i32 s99, s99, s98
	s_lshr_b32 s98, s26, 4
	s_lshl_b32 s98, s98, 2
	s_add_i32 s26, s99, s98
